# combo10 + attention epilogue: 16 per-row 1/l LDS reads replaced by four 16-byte reads up front
# speedup vs baseline: 1.0097x; 1.0097x over previous
.LBB0_1633:
	s_add_i32 s77, s77, s45
	v_mov_b32_e32 v68, s77
	v_mov_b32_e32 v65, v167
	v_mov_b32_e32 v67, v166
	v_mov_b32_e32 v66, v64
	s_nop 1
	v_permlane32_swap_b32_e32 v64, v66
	v_cmp_eq_u32_e32 vcc, 0, v67
	s_and_saveexec_b64 s[48:49], vcc
	v_lshl_add_u32 v69, v65, 2, s3
	v_add_f32_e32 v64, v64, v66
	ds_write_b32 v69, v64
	s_or_b64 exec, exec, s[48:49]
	s_waitcnt lgkmcnt(0)
	v_lshl_add_u32 v71, v67, 4, s3
	ds_read_b128 v[236:239], v71
	ds_read_b128 v[240:243], v71 offset:32
	ds_read_b128 v[244:247], v71 offset:64
	ds_read_b128 v[248:251], v71 offset:96
	v_lshl_add_u32 v70, v65, 1, s56
	v_ashrrev_i32_e32 v69, 31, v68
	v_lshlrev_b32_e32 v66, 2, v67
	v_cmp_eq_u32_e32 vcc, 0, v65
	s_waitcnt lgkmcnt(0)
	v_rcp_f32_e32 v72, v236
	v_lshl_add_u64 v[64:65], s[20:21], 0, v[68:69]
	v_lshl_add_u32 v67, v67, 10, v70
	v_mul_f32_e32 v68, v72, v48
	v_fma_mixlo_f16 v48, v72, v48, 0
	ds_write_b16 v67, v48
	v_mul_f32_e32 v48, v72, v32
	v_mul_f32_e32 v48, v48, v48
	v_fma_mixlo_f16 v32, v72, v32, 0
	v_fmac_f32_e32 v48, v68, v68
	ds_write_b16 v67, v32 offset:64
	v_mul_f32_e32 v32, v72, v16
	v_fma_mixlo_f16 v16, v72, v16, 0
	v_fmac_f32_e32 v48, v32, v32
	ds_write_b16 v67, v16 offset:128
	v_mul_f32_e32 v16, v72, v0
	v_fmac_f32_e32 v48, v16, v16
	v_fma_mixlo_f16 v0, v72, v0, 0
	ds_write_b16 v67, v0 offset:192
	s_nop 0
	v_add_f32_dpp v0, v48, v48 quad_perm:[1,0,3,2] row_mask:0xf bank_mask:0xf bound_ctrl:1
	s_nop 1
	v_add_f32_dpp v0, v0, v0 quad_perm:[2,3,0,1] row_mask:0xf bank_mask:0xf bound_ctrl:1
	s_nop 1
	v_add_f32_dpp v0, v0, v0 row_half_mirror row_mask:0xf bank_mask:0xf bound_ctrl:1
	s_nop 1
	v_add_f32_dpp v0, v0, v0 row_mirror row_mask:0xf bank_mask:0xf bound_ctrl:1
	v_mov_b32_e32 v16, v0
	s_nop 1
	v_permlane16_swap_b32_e32 v0, v16
	s_and_saveexec_b64 s[48:49], vcc
	s_cbranch_execz .LBB0_1637
	v_ashrrev_i32_e32 v67, 31, v66
	v_lshl_add_u64 v[68:69], v[64:65], 0, v[66:67]
	v_lshlrev_b64 v[68:69], 6, v[68:69]
	v_add_f32_e32 v0, v0, v16
	v_lshl_add_u64 v[68:69], s[24:25], 0, v[68:69]
	global_store_dword v[68:69], v0, off
.LBB0_1637:
	s_or_b64 exec, exec, s[48:49]
	v_rcp_f32_e32 v16, v237
	v_or_b32_e32 v0, 1, v66
	v_lshl_add_u32 v32, v0, 8, v70
	v_mul_f32_e32 v48, v16, v49
	v_fma_mixlo_f16 v49, v16, v49, 0
	v_mul_f32_e32 v67, v16, v33
	v_fma_mixlo_f16 v33, v16, v33, 0
	ds_write_b16 v32, v49
	v_mul_f32_e32 v49, v67, v67
	ds_write_b16 v32, v33 offset:64
	v_fmac_f32_e32 v49, v48, v48
	v_mul_f32_e32 v33, v16, v17
	v_fma_mixlo_f16 v17, v16, v17, 0
	v_fmac_f32_e32 v49, v33, v33
	ds_write_b16 v32, v17 offset:128
	v_mul_f32_e32 v17, v16, v1
	v_fmac_f32_e32 v49, v17, v17
	v_fma_mixlo_f16 v1, v16, v1, 0
	ds_write_b16 v32, v1 offset:192
	s_nop 0
	v_add_f32_dpp v1, v49, v49 quad_perm:[1,0,3,2] row_mask:0xf bank_mask:0xf bound_ctrl:1
	s_nop 1
	v_add_f32_dpp v1, v1, v1 quad_perm:[2,3,0,1] row_mask:0xf bank_mask:0xf bound_ctrl:1
	s_nop 1
	v_add_f32_dpp v1, v1, v1 row_half_mirror row_mask:0xf bank_mask:0xf bound_ctrl:1
	s_nop 1
	v_add_f32_dpp v16, v1, v1 row_mirror row_mask:0xf bank_mask:0xf bound_ctrl:1
	v_mov_b32_e32 v17, v16
	s_nop 1
	v_permlane16_swap_b32_e32 v16, v17
	s_and_saveexec_b64 s[48:49], vcc
	s_cbranch_execz .LBB0_1639
	v_ashrrev_i32_e32 v1, 31, v0
	v_lshl_add_u64 v[0:1], v[64:65], 0, v[0:1]
	v_lshlrev_b64 v[0:1], 6, v[0:1]
	v_add_f32_e32 v16, v16, v17
	v_lshl_add_u64 v[0:1], s[24:25], 0, v[0:1]
	global_store_dword v[0:1], v16, off
.LBB0_1639:
	s_or_b64 exec, exec, s[48:49]
	v_rcp_f32_e32 v1, v238
	v_or_b32_e32 v0, 2, v66
	v_lshl_add_u32 v16, v0, 8, v70
	v_fma_mixlo_f16 v32, v1, v50, 0
	v_mul_f32_e32 v33, v1, v34
	v_mul_f32_e32 v17, v1, v50
	ds_write_b16 v16, v32
	v_mul_f32_e32 v32, v33, v33
	v_fmac_f32_e32 v32, v17, v17
	v_mul_f32_e32 v17, v1, v18
	v_fmac_f32_e32 v32, v17, v17
	v_fma_mixlo_f16 v17, v1, v18, 0
	ds_write_b16 v16, v17 offset:128
	v_mul_f32_e32 v17, v1, v2
	v_fma_mixlo_f16 v34, v1, v34, 0
	v_fmac_f32_e32 v32, v17, v17
	v_fma_mixlo_f16 v1, v1, v2, 0
	ds_write_b16 v16, v1 offset:192
	ds_write_b16 v16, v34 offset:64
	v_add_f32_dpp v1, v32, v32 quad_perm:[1,0,3,2] row_mask:0xf bank_mask:0xf bound_ctrl:1
	s_nop 1
	v_add_f32_dpp v1, v1, v1 quad_perm:[2,3,0,1] row_mask:0xf bank_mask:0xf bound_ctrl:1
	s_nop 1
	v_add_f32_dpp v1, v1, v1 row_half_mirror row_mask:0xf bank_mask:0xf bound_ctrl:1
	s_nop 1
	v_add_f32_dpp v2, v1, v1 row_mirror row_mask:0xf bank_mask:0xf bound_ctrl:1
	v_mov_b32_e32 v16, v2
	s_nop 1
	v_permlane16_swap_b32_e32 v2, v16
	s_and_saveexec_b64 s[48:49], vcc
	s_cbranch_execz .LBB0_1641
	v_ashrrev_i32_e32 v1, 31, v0
	v_lshl_add_u64 v[0:1], v[64:65], 0, v[0:1]
	v_lshlrev_b64 v[0:1], 6, v[0:1]
	v_add_f32_e32 v2, v2, v16
	v_lshl_add_u64 v[0:1], s[24:25], 0, v[0:1]
	global_store_dword v[0:1], v2, off
.LBB0_1641:
	s_or_b64 exec, exec, s[48:49]
	v_rcp_f32_e32 v1, v239
	v_or_b32_e32 v0, 3, v66
	v_lshl_add_u32 v2, v0, 8, v70
	v_fma_mixlo_f16 v17, v1, v51, 0
	v_mul_f32_e32 v18, v1, v35
	v_mul_f32_e32 v16, v1, v51
	ds_write_b16 v2, v17
	v_mul_f32_e32 v17, v18, v18
	v_fmac_f32_e32 v17, v16, v16
	v_mul_f32_e32 v16, v1, v19
	v_fmac_f32_e32 v17, v16, v16
	v_fma_mixlo_f16 v16, v1, v19, 0
	ds_write_b16 v2, v16 offset:128
	v_mul_f32_e32 v16, v1, v3
	v_fma_mixlo_f16 v32, v1, v35, 0
	v_fmac_f32_e32 v17, v16, v16
	v_fma_mixlo_f16 v1, v1, v3, 0
	ds_write_b16 v2, v1 offset:192
	ds_write_b16 v2, v32 offset:64
	v_add_f32_dpp v1, v17, v17 quad_perm:[1,0,3,2] row_mask:0xf bank_mask:0xf bound_ctrl:1
	s_nop 1
	v_add_f32_dpp v1, v1, v1 quad_perm:[2,3,0,1] row_mask:0xf bank_mask:0xf bound_ctrl:1
	s_nop 1
	v_add_f32_dpp v1, v1, v1 row_half_mirror row_mask:0xf bank_mask:0xf bound_ctrl:1
	s_nop 1
	v_add_f32_dpp v2, v1, v1 row_mirror row_mask:0xf bank_mask:0xf bound_ctrl:1
	v_mov_b32_e32 v3, v2
	s_nop 1
	v_permlane16_swap_b32_e32 v2, v3
	s_and_saveexec_b64 s[48:49], vcc
	s_cbranch_execz .LBB0_1643
	v_ashrrev_i32_e32 v1, 31, v0
	v_lshl_add_u64 v[0:1], v[64:65], 0, v[0:1]
	v_lshlrev_b64 v[0:1], 6, v[0:1]
	v_add_f32_e32 v2, v2, v3
	v_lshl_add_u64 v[0:1], s[24:25], 0, v[0:1]
	global_store_dword v[0:1], v2, off
.LBB0_1643:
	s_or_b64 exec, exec, s[48:49]
	v_rcp_f32_e32 v1, v240
	v_add_u32_e32 v0, 8, v66
	v_lshl_add_u32 v2, v0, 8, v70
	v_fma_mixlo_f16 v16, v1, v52, 0
	v_mul_f32_e32 v17, v1, v36
	v_mul_f32_e32 v3, v1, v52
	ds_write_b16 v2, v16
	v_mul_f32_e32 v16, v17, v17
	v_fmac_f32_e32 v16, v3, v3
	v_mul_f32_e32 v3, v1, v20
	v_fmac_f32_e32 v16, v3, v3
	v_fma_mixlo_f16 v3, v1, v20, 0
	ds_write_b16 v2, v3 offset:128
	v_mul_f32_e32 v3, v1, v4
	v_fma_mixlo_f16 v18, v1, v36, 0
	v_fmac_f32_e32 v16, v3, v3
	v_fma_mixlo_f16 v1, v1, v4, 0
	ds_write_b16 v2, v1 offset:192
	ds_write_b16 v2, v18 offset:64
	v_add_f32_dpp v1, v16, v16 quad_perm:[1,0,3,2] row_mask:0xf bank_mask:0xf bound_ctrl:1
	s_nop 1
	v_add_f32_dpp v1, v1, v1 quad_perm:[2,3,0,1] row_mask:0xf bank_mask:0xf bound_ctrl:1
	s_nop 1
	v_add_f32_dpp v1, v1, v1 row_half_mirror row_mask:0xf bank_mask:0xf bound_ctrl:1
	s_nop 1
	v_add_f32_dpp v2, v1, v1 row_mirror row_mask:0xf bank_mask:0xf bound_ctrl:1
	v_mov_b32_e32 v3, v2
	s_nop 1
	v_permlane16_swap_b32_e32 v2, v3
	s_and_saveexec_b64 s[48:49], vcc
	s_cbranch_execz .LBB0_1645
	v_ashrrev_i32_e32 v1, 31, v0
	v_lshl_add_u64 v[0:1], v[64:65], 0, v[0:1]
	v_lshlrev_b64 v[0:1], 6, v[0:1]
	v_add_f32_e32 v2, v2, v3
	v_lshl_add_u64 v[0:1], s[24:25], 0, v[0:1]
	global_store_dword v[0:1], v2, off
.LBB0_1645:
	s_or_b64 exec, exec, s[48:49]
	v_rcp_f32_e32 v1, v241
	v_add_u32_e32 v0, 9, v66
	v_lshl_add_u32 v2, v0, 8, v70
	v_fma_mixlo_f16 v4, v1, v53, 0
	v_mul_f32_e32 v16, v1, v37
	v_mul_f32_e32 v3, v1, v53
	ds_write_b16 v2, v4
	v_mul_f32_e32 v4, v16, v16
	v_fmac_f32_e32 v4, v3, v3
	v_mul_f32_e32 v3, v1, v21
	v_fmac_f32_e32 v4, v3, v3
	v_fma_mixlo_f16 v3, v1, v21, 0
	ds_write_b16 v2, v3 offset:128
	v_mul_f32_e32 v3, v1, v5
	v_fma_mixlo_f16 v17, v1, v37, 0
	v_fmac_f32_e32 v4, v3, v3
	v_fma_mixlo_f16 v1, v1, v5, 0
	ds_write_b16 v2, v1 offset:192
	ds_write_b16 v2, v17 offset:64
	v_add_f32_dpp v1, v4, v4 quad_perm:[1,0,3,2] row_mask:0xf bank_mask:0xf bound_ctrl:1
	s_nop 1
	v_add_f32_dpp v1, v1, v1 quad_perm:[2,3,0,1] row_mask:0xf bank_mask:0xf bound_ctrl:1
	s_nop 1
	v_add_f32_dpp v1, v1, v1 row_half_mirror row_mask:0xf bank_mask:0xf bound_ctrl:1
	s_nop 1
	v_add_f32_dpp v2, v1, v1 row_mirror row_mask:0xf bank_mask:0xf bound_ctrl:1
	v_mov_b32_e32 v3, v2
	s_nop 1
	v_permlane16_swap_b32_e32 v2, v3
	s_and_saveexec_b64 s[48:49], vcc
	s_cbranch_execz .LBB0_1647
	v_ashrrev_i32_e32 v1, 31, v0
	v_lshl_add_u64 v[0:1], v[64:65], 0, v[0:1]
	v_lshlrev_b64 v[0:1], 6, v[0:1]
	v_add_f32_e32 v2, v2, v3
	v_lshl_add_u64 v[0:1], s[24:25], 0, v[0:1]
	global_store_dword v[0:1], v2, off
.LBB0_1647:
	s_or_b64 exec, exec, s[48:49]
	v_rcp_f32_e32 v1, v242
	v_add_u32_e32 v0, 10, v66
	v_lshl_add_u32 v2, v0, 8, v70
	v_fma_mixlo_f16 v4, v1, v54, 0
	v_mul_f32_e32 v5, v1, v38
	v_mul_f32_e32 v3, v1, v54
	ds_write_b16 v2, v4
	v_mul_f32_e32 v4, v5, v5
	v_fmac_f32_e32 v4, v3, v3
	v_mul_f32_e32 v3, v1, v22
	v_fmac_f32_e32 v4, v3, v3
	v_fma_mixlo_f16 v3, v1, v22, 0
	ds_write_b16 v2, v3 offset:128
	v_mul_f32_e32 v3, v1, v6
	v_fma_mixlo_f16 v16, v1, v38, 0
	v_fmac_f32_e32 v4, v3, v3
	v_fma_mixlo_f16 v1, v1, v6, 0
	ds_write_b16 v2, v1 offset:192
	ds_write_b16 v2, v16 offset:64
	v_add_f32_dpp v1, v4, v4 quad_perm:[1,0,3,2] row_mask:0xf bank_mask:0xf bound_ctrl:1
	s_nop 1
	v_add_f32_dpp v1, v1, v1 quad_perm:[2,3,0,1] row_mask:0xf bank_mask:0xf bound_ctrl:1
	s_nop 1
	v_add_f32_dpp v1, v1, v1 row_half_mirror row_mask:0xf bank_mask:0xf bound_ctrl:1
	s_nop 1
	v_add_f32_dpp v2, v1, v1 row_mirror row_mask:0xf bank_mask:0xf bound_ctrl:1
	v_mov_b32_e32 v3, v2
	s_nop 1
	v_permlane16_swap_b32_e32 v2, v3
	s_and_saveexec_b64 s[48:49], vcc
	s_cbranch_execz .LBB0_1649
	v_ashrrev_i32_e32 v1, 31, v0
	v_lshl_add_u64 v[0:1], v[64:65], 0, v[0:1]
	v_lshlrev_b64 v[0:1], 6, v[0:1]
	v_add_f32_e32 v2, v2, v3
	v_lshl_add_u64 v[0:1], s[24:25], 0, v[0:1]
	global_store_dword v[0:1], v2, off
.LBB0_1649:
	s_or_b64 exec, exec, s[48:49]
	v_rcp_f32_e32 v1, v243
	v_add_u32_e32 v0, 11, v66
	v_lshl_add_u32 v2, v0, 8, v70
	v_fma_mixlo_f16 v4, v1, v55, 0
	v_mul_f32_e32 v5, v1, v39
	v_mul_f32_e32 v3, v1, v55
	ds_write_b16 v2, v4
	v_mul_f32_e32 v4, v5, v5
	v_fmac_f32_e32 v4, v3, v3
	v_mul_f32_e32 v3, v1, v23
	v_fmac_f32_e32 v4, v3, v3
	v_fma_mixlo_f16 v3, v1, v23, 0
	ds_write_b16 v2, v3 offset:128
	v_mul_f32_e32 v3, v1, v7
	v_fma_mixlo_f16 v6, v1, v39, 0
	v_fmac_f32_e32 v4, v3, v3
	v_fma_mixlo_f16 v1, v1, v7, 0
	ds_write_b16 v2, v1 offset:192
	ds_write_b16 v2, v6 offset:64
	v_add_f32_dpp v1, v4, v4 quad_perm:[1,0,3,2] row_mask:0xf bank_mask:0xf bound_ctrl:1
	s_nop 1
	v_add_f32_dpp v1, v1, v1 quad_perm:[2,3,0,1] row_mask:0xf bank_mask:0xf bound_ctrl:1
	s_nop 1
	v_add_f32_dpp v1, v1, v1 row_half_mirror row_mask:0xf bank_mask:0xf bound_ctrl:1
	s_nop 1
	v_add_f32_dpp v2, v1, v1 row_mirror row_mask:0xf bank_mask:0xf bound_ctrl:1
	v_mov_b32_e32 v3, v2
	s_nop 1
	v_permlane16_swap_b32_e32 v2, v3
	s_and_saveexec_b64 s[48:49], vcc
	s_cbranch_execz .LBB0_1651
	v_ashrrev_i32_e32 v1, 31, v0
	v_lshl_add_u64 v[0:1], v[64:65], 0, v[0:1]
	v_lshlrev_b64 v[0:1], 6, v[0:1]
	v_add_f32_e32 v2, v2, v3
	v_lshl_add_u64 v[0:1], s[24:25], 0, v[0:1]
	global_store_dword v[0:1], v2, off
.LBB0_1651:
	s_or_b64 exec, exec, s[48:49]
	v_rcp_f32_e32 v1, v244
	v_add_u32_e32 v0, 16, v66
	v_lshl_add_u32 v2, v0, 8, v70
	v_fma_mixlo_f16 v4, v1, v56, 0
	v_mul_f32_e32 v5, v1, v40
	v_mul_f32_e32 v3, v1, v56
	ds_write_b16 v2, v4
	v_mul_f32_e32 v4, v5, v5
	v_fmac_f32_e32 v4, v3, v3
	v_mul_f32_e32 v3, v1, v24
	v_fmac_f32_e32 v4, v3, v3
	v_fma_mixlo_f16 v3, v1, v24, 0
	ds_write_b16 v2, v3 offset:128
	v_mul_f32_e32 v3, v1, v8
	v_fma_mixlo_f16 v6, v1, v40, 0
	v_fmac_f32_e32 v4, v3, v3
	v_fma_mixlo_f16 v1, v1, v8, 0
	ds_write_b16 v2, v1 offset:192
	ds_write_b16 v2, v6 offset:64
	v_add_f32_dpp v1, v4, v4 quad_perm:[1,0,3,2] row_mask:0xf bank_mask:0xf bound_ctrl:1
	s_nop 1
	v_add_f32_dpp v1, v1, v1 quad_perm:[2,3,0,1] row_mask:0xf bank_mask:0xf bound_ctrl:1
	s_nop 1
	v_add_f32_dpp v1, v1, v1 row_half_mirror row_mask:0xf bank_mask:0xf bound_ctrl:1
	s_nop 1
	v_add_f32_dpp v2, v1, v1 row_mirror row_mask:0xf bank_mask:0xf bound_ctrl:1
	v_mov_b32_e32 v3, v2
	s_nop 1
	v_permlane16_swap_b32_e32 v2, v3
	s_and_saveexec_b64 s[48:49], vcc
	s_cbranch_execz .LBB0_1653
	v_ashrrev_i32_e32 v1, 31, v0
	v_lshl_add_u64 v[0:1], v[64:65], 0, v[0:1]
	v_lshlrev_b64 v[0:1], 6, v[0:1]
	v_add_f32_e32 v2, v2, v3
	v_lshl_add_u64 v[0:1], s[24:25], 0, v[0:1]
	global_store_dword v[0:1], v2, off
.LBB0_1653:
	s_or_b64 exec, exec, s[48:49]
	v_rcp_f32_e32 v1, v245
	v_add_u32_e32 v0, 17, v66
	v_lshl_add_u32 v2, v0, 8, v70
	v_fma_mixlo_f16 v4, v1, v57, 0
	v_mul_f32_e32 v5, v1, v41
	v_mul_f32_e32 v3, v1, v57
	ds_write_b16 v2, v4
	v_mul_f32_e32 v4, v5, v5
	v_fmac_f32_e32 v4, v3, v3
	v_mul_f32_e32 v3, v1, v25
	v_fmac_f32_e32 v4, v3, v3
	v_fma_mixlo_f16 v3, v1, v25, 0
	ds_write_b16 v2, v3 offset:128
	v_mul_f32_e32 v3, v1, v9
	v_fma_mixlo_f16 v6, v1, v41, 0
	v_fmac_f32_e32 v4, v3, v3
	v_fma_mixlo_f16 v1, v1, v9, 0
	ds_write_b16 v2, v1 offset:192
	ds_write_b16 v2, v6 offset:64
	v_add_f32_dpp v1, v4, v4 quad_perm:[1,0,3,2] row_mask:0xf bank_mask:0xf bound_ctrl:1
	s_nop 1
	v_add_f32_dpp v1, v1, v1 quad_perm:[2,3,0,1] row_mask:0xf bank_mask:0xf bound_ctrl:1
	s_nop 1
	v_add_f32_dpp v1, v1, v1 row_half_mirror row_mask:0xf bank_mask:0xf bound_ctrl:1
	s_nop 1
	v_add_f32_dpp v2, v1, v1 row_mirror row_mask:0xf bank_mask:0xf bound_ctrl:1
	v_mov_b32_e32 v3, v2
	s_nop 1
	v_permlane16_swap_b32_e32 v2, v3
	s_and_saveexec_b64 s[48:49], vcc
	s_cbranch_execz .LBB0_1655
	v_ashrrev_i32_e32 v1, 31, v0
	v_lshl_add_u64 v[0:1], v[64:65], 0, v[0:1]
	v_lshlrev_b64 v[0:1], 6, v[0:1]
	v_add_f32_e32 v2, v2, v3
	v_lshl_add_u64 v[0:1], s[24:25], 0, v[0:1]
	global_store_dword v[0:1], v2, off
.LBB0_1655:
	s_or_b64 exec, exec, s[48:49]
	v_rcp_f32_e32 v1, v246
	v_add_u32_e32 v0, 18, v66
	v_lshl_add_u32 v2, v0, 8, v70
	v_fma_mixlo_f16 v4, v1, v58, 0
	v_mul_f32_e32 v5, v1, v42
	v_mul_f32_e32 v3, v1, v58
	ds_write_b16 v2, v4
	v_mul_f32_e32 v4, v5, v5
	v_fmac_f32_e32 v4, v3, v3
	v_mul_f32_e32 v3, v1, v26
	v_fmac_f32_e32 v4, v3, v3
	v_fma_mixlo_f16 v3, v1, v26, 0
	ds_write_b16 v2, v3 offset:128
	v_mul_f32_e32 v3, v1, v10
	v_fma_mixlo_f16 v6, v1, v42, 0
	v_fmac_f32_e32 v4, v3, v3
	v_fma_mixlo_f16 v1, v1, v10, 0
	ds_write_b16 v2, v1 offset:192
	ds_write_b16 v2, v6 offset:64
	v_add_f32_dpp v1, v4, v4 quad_perm:[1,0,3,2] row_mask:0xf bank_mask:0xf bound_ctrl:1
	s_nop 1
	v_add_f32_dpp v1, v1, v1 quad_perm:[2,3,0,1] row_mask:0xf bank_mask:0xf bound_ctrl:1
	s_nop 1
	v_add_f32_dpp v1, v1, v1 row_half_mirror row_mask:0xf bank_mask:0xf bound_ctrl:1
	s_nop 1
	v_add_f32_dpp v2, v1, v1 row_mirror row_mask:0xf bank_mask:0xf bound_ctrl:1
	v_mov_b32_e32 v3, v2
	s_nop 1
	v_permlane16_swap_b32_e32 v2, v3
	s_and_saveexec_b64 s[48:49], vcc
	s_cbranch_execz .LBB0_1657
	v_ashrrev_i32_e32 v1, 31, v0
	v_lshl_add_u64 v[0:1], v[64:65], 0, v[0:1]
	v_lshlrev_b64 v[0:1], 6, v[0:1]
	v_add_f32_e32 v2, v2, v3
	v_lshl_add_u64 v[0:1], s[24:25], 0, v[0:1]
	global_store_dword v[0:1], v2, off
.LBB0_1657:
	s_or_b64 exec, exec, s[48:49]
	v_rcp_f32_e32 v1, v247
	v_add_u32_e32 v0, 19, v66
	v_lshl_add_u32 v2, v0, 8, v70
	v_fma_mixlo_f16 v4, v1, v59, 0
	v_mul_f32_e32 v5, v1, v43
	v_mul_f32_e32 v3, v1, v59
	ds_write_b16 v2, v4
	v_mul_f32_e32 v4, v5, v5
	v_fmac_f32_e32 v4, v3, v3
	v_mul_f32_e32 v3, v1, v27
	v_fmac_f32_e32 v4, v3, v3
	v_fma_mixlo_f16 v3, v1, v27, 0
	ds_write_b16 v2, v3 offset:128
	v_mul_f32_e32 v3, v1, v11
	v_fma_mixlo_f16 v6, v1, v43, 0
	v_fmac_f32_e32 v4, v3, v3
	v_fma_mixlo_f16 v1, v1, v11, 0
	ds_write_b16 v2, v1 offset:192
	ds_write_b16 v2, v6 offset:64
	v_add_f32_dpp v1, v4, v4 quad_perm:[1,0,3,2] row_mask:0xf bank_mask:0xf bound_ctrl:1
	s_nop 1
	v_add_f32_dpp v1, v1, v1 quad_perm:[2,3,0,1] row_mask:0xf bank_mask:0xf bound_ctrl:1
	s_nop 1
	v_add_f32_dpp v1, v1, v1 row_half_mirror row_mask:0xf bank_mask:0xf bound_ctrl:1
	s_nop 1
	v_add_f32_dpp v2, v1, v1 row_mirror row_mask:0xf bank_mask:0xf bound_ctrl:1
	v_mov_b32_e32 v3, v2
	s_nop 1
	v_permlane16_swap_b32_e32 v2, v3
	s_and_saveexec_b64 s[48:49], vcc
	s_cbranch_execz .LBB0_1659
	v_ashrrev_i32_e32 v1, 31, v0
	v_lshl_add_u64 v[0:1], v[64:65], 0, v[0:1]
	v_lshlrev_b64 v[0:1], 6, v[0:1]
	v_add_f32_e32 v2, v2, v3
	v_lshl_add_u64 v[0:1], s[24:25], 0, v[0:1]
	global_store_dword v[0:1], v2, off
.LBB0_1659:
	s_or_b64 exec, exec, s[48:49]
	v_rcp_f32_e32 v1, v248
	v_add_u32_e32 v0, 24, v66
	v_lshl_add_u32 v2, v0, 8, v70
	v_fma_mixlo_f16 v4, v1, v60, 0
	v_mul_f32_e32 v5, v1, v44
	v_mul_f32_e32 v3, v1, v60
	ds_write_b16 v2, v4
	v_mul_f32_e32 v4, v5, v5
	v_fmac_f32_e32 v4, v3, v3
	v_mul_f32_e32 v3, v1, v28
	v_fmac_f32_e32 v4, v3, v3
	v_fma_mixlo_f16 v3, v1, v28, 0
	ds_write_b16 v2, v3 offset:128
	v_mul_f32_e32 v3, v1, v12
	v_fma_mixlo_f16 v6, v1, v44, 0
	v_fmac_f32_e32 v4, v3, v3
	v_fma_mixlo_f16 v1, v1, v12, 0
	ds_write_b16 v2, v1 offset:192
	ds_write_b16 v2, v6 offset:64
	v_add_f32_dpp v1, v4, v4 quad_perm:[1,0,3,2] row_mask:0xf bank_mask:0xf bound_ctrl:1
	s_nop 1
	v_add_f32_dpp v1, v1, v1 quad_perm:[2,3,0,1] row_mask:0xf bank_mask:0xf bound_ctrl:1
	s_nop 1
	v_add_f32_dpp v1, v1, v1 row_half_mirror row_mask:0xf bank_mask:0xf bound_ctrl:1
	s_nop 1
	v_add_f32_dpp v2, v1, v1 row_mirror row_mask:0xf bank_mask:0xf bound_ctrl:1
	v_mov_b32_e32 v3, v2
	s_nop 1
	v_permlane16_swap_b32_e32 v2, v3
	s_and_saveexec_b64 s[48:49], vcc
	s_cbranch_execz .LBB0_1661
	v_ashrrev_i32_e32 v1, 31, v0
	v_lshl_add_u64 v[0:1], v[64:65], 0, v[0:1]
	v_lshlrev_b64 v[0:1], 6, v[0:1]
	v_add_f32_e32 v2, v2, v3
	v_lshl_add_u64 v[0:1], s[24:25], 0, v[0:1]
	global_store_dword v[0:1], v2, off
.LBB0_1661:
	s_or_b64 exec, exec, s[48:49]
	v_rcp_f32_e32 v1, v249
	v_add_u32_e32 v0, 25, v66
	v_lshl_add_u32 v2, v0, 8, v70
	v_fma_mixlo_f16 v4, v1, v61, 0
	v_mul_f32_e32 v5, v1, v45
	v_mul_f32_e32 v3, v1, v61
	ds_write_b16 v2, v4
	v_mul_f32_e32 v4, v5, v5
	v_fmac_f32_e32 v4, v3, v3
	v_mul_f32_e32 v3, v1, v29
	v_fmac_f32_e32 v4, v3, v3
	v_fma_mixlo_f16 v3, v1, v29, 0
	ds_write_b16 v2, v3 offset:128
	v_mul_f32_e32 v3, v1, v13
	v_fma_mixlo_f16 v6, v1, v45, 0
	v_fmac_f32_e32 v4, v3, v3
	v_fma_mixlo_f16 v1, v1, v13, 0
	ds_write_b16 v2, v1 offset:192
	ds_write_b16 v2, v6 offset:64
	v_add_f32_dpp v1, v4, v4 quad_perm:[1,0,3,2] row_mask:0xf bank_mask:0xf bound_ctrl:1
	s_nop 1
	v_add_f32_dpp v1, v1, v1 quad_perm:[2,3,0,1] row_mask:0xf bank_mask:0xf bound_ctrl:1
	s_nop 1
	v_add_f32_dpp v1, v1, v1 row_half_mirror row_mask:0xf bank_mask:0xf bound_ctrl:1
	s_nop 1
	v_add_f32_dpp v2, v1, v1 row_mirror row_mask:0xf bank_mask:0xf bound_ctrl:1
	v_mov_b32_e32 v3, v2
	s_nop 1
	v_permlane16_swap_b32_e32 v2, v3
	s_and_saveexec_b64 s[48:49], vcc
	s_cbranch_execz .LBB0_1663
	v_ashrrev_i32_e32 v1, 31, v0
	v_lshl_add_u64 v[0:1], v[64:65], 0, v[0:1]
	v_lshlrev_b64 v[0:1], 6, v[0:1]
	v_add_f32_e32 v2, v2, v3
	v_lshl_add_u64 v[0:1], s[24:25], 0, v[0:1]
	global_store_dword v[0:1], v2, off
.LBB0_1663:
	s_or_b64 exec, exec, s[48:49]
	v_rcp_f32_e32 v1, v250
	v_add_u32_e32 v0, 26, v66
	v_lshl_add_u32 v2, v0, 8, v70
	v_fma_mixlo_f16 v4, v1, v62, 0
	v_mul_f32_e32 v5, v1, v46
	v_mul_f32_e32 v3, v1, v62
	ds_write_b16 v2, v4
	v_mul_f32_e32 v4, v5, v5
	v_fmac_f32_e32 v4, v3, v3
	v_mul_f32_e32 v3, v1, v30
	v_fmac_f32_e32 v4, v3, v3
	v_fma_mixlo_f16 v3, v1, v30, 0
	ds_write_b16 v2, v3 offset:128
	v_mul_f32_e32 v3, v1, v14
	v_fma_mixlo_f16 v6, v1, v46, 0
	v_fmac_f32_e32 v4, v3, v3
	v_fma_mixlo_f16 v1, v1, v14, 0
	ds_write_b16 v2, v1 offset:192
	ds_write_b16 v2, v6 offset:64
	v_add_f32_dpp v1, v4, v4 quad_perm:[1,0,3,2] row_mask:0xf bank_mask:0xf bound_ctrl:1
	s_nop 1
	v_add_f32_dpp v1, v1, v1 quad_perm:[2,3,0,1] row_mask:0xf bank_mask:0xf bound_ctrl:1
	s_nop 1
	v_add_f32_dpp v1, v1, v1 row_half_mirror row_mask:0xf bank_mask:0xf bound_ctrl:1
	s_nop 1
	v_add_f32_dpp v2, v1, v1 row_mirror row_mask:0xf bank_mask:0xf bound_ctrl:1
	v_mov_b32_e32 v3, v2
	s_nop 1
	v_permlane16_swap_b32_e32 v2, v3
	s_and_saveexec_b64 s[48:49], vcc
	s_cbranch_execz .LBB0_1665
	v_ashrrev_i32_e32 v1, 31, v0
	v_lshl_add_u64 v[0:1], v[64:65], 0, v[0:1]
	v_lshlrev_b64 v[0:1], 6, v[0:1]
	v_add_f32_e32 v2, v2, v3
	v_lshl_add_u64 v[0:1], s[24:25], 0, v[0:1]
	global_store_dword v[0:1], v2, off
.LBB0_1665:
	s_or_b64 exec, exec, s[48:49]
	v_rcp_f32_e32 v1, v251
	v_add_u32_e32 v0, 27, v66
	v_lshl_add_u32 v2, v0, 8, v70
	v_fma_mixlo_f16 v4, v1, v63, 0
	v_mul_f32_e32 v5, v1, v47
	v_mul_f32_e32 v3, v1, v63
	ds_write_b16 v2, v4
	v_mul_f32_e32 v4, v5, v5
	v_fmac_f32_e32 v4, v3, v3
	v_mul_f32_e32 v3, v1, v31
	v_fmac_f32_e32 v4, v3, v3
	v_fma_mixlo_f16 v3, v1, v31, 0
	ds_write_b16 v2, v3 offset:128
	v_mul_f32_e32 v3, v1, v15
	v_fma_mixlo_f16 v6, v1, v47, 0
	v_fmac_f32_e32 v4, v3, v3
	v_fma_mixlo_f16 v1, v1, v15, 0
	ds_write_b16 v2, v1 offset:192
	ds_write_b16 v2, v6 offset:64
	v_add_f32_dpp v1, v4, v4 quad_perm:[1,0,3,2] row_mask:0xf bank_mask:0xf bound_ctrl:1
	s_nop 1
	v_add_f32_dpp v1, v1, v1 quad_perm:[2,3,0,1] row_mask:0xf bank_mask:0xf bound_ctrl:1
	s_nop 1
	v_add_f32_dpp v1, v1, v1 row_half_mirror row_mask:0xf bank_mask:0xf bound_ctrl:1
	s_nop 1
	v_add_f32_dpp v2, v1, v1 row_mirror row_mask:0xf bank_mask:0xf bound_ctrl:1
	v_mov_b32_e32 v3, v2
	s_nop 1
	v_permlane16_swap_b32_e32 v2, v3
	s_and_saveexec_b64 s[48:49], vcc
	s_cbranch_execz .LBB0_1619
	v_ashrrev_i32_e32 v1, 31, v0
	v_lshl_add_u64 v[0:1], v[64:65], 0, v[0:1]
	v_lshlrev_b64 v[0:1], 6, v[0:1]
	v_add_f32_e32 v2, v2, v3
	v_lshl_add_u64 v[0:1], s[24:25], 0, v[0:1]
	global_store_dword v[0:1], v2, off
	s_branch .LBB0_1619
